# conv: removed the vmcnt(0) that split its loads into two round trips; accumulator zeroing 128 x v_mov_b32 -> 64 x v_mov_b64 per tile
# speedup vs baseline: 1.0196x; 1.0033x over previous
; template <class Epi, class Sched, bool ALIGN_EPI = false, bool SP2 = false, bool ATILED = false, bool BTILED = false>
; __device__ __forceinline__ void gemm_phase(PG8_LAS unsigned char* lds, const Gemm g, const Sched& S, const Epi& E, const int tid) {
;     ...
;         const bool has_next = S.next(ui + 1, nxt);
;         const char* nA = has_next ? (const char*)g.A + (size_t)nxt.pm * tstepA : cA; const char* nB = has_next ? (const char*)g.Bt + (size_t)nxt.pn * tstepB : cB;
;     ...
; #pragma unroll
;         for (int a = 0; a < 2; ++a)
; #pragma unroll
;             for (int b = 0; b < 2; ++b)
; #pragma unroll
;                 for (int m = 0; m < 4; ++m)
; #pragma unroll
;                     for (int n = 0; n < 2; ++n) acc[a][b][m][n] = (f32x4){0.f, 0.f, 0.f, 0.f};
;         cur = nxt; cA = nA; cB = nB; ++ui;
.LBB0_165:
	s_ashr_i32 s15, s14, 31
	s_lshl_b64 s[24:25], s[14:15], 19
	s_add_u32 s24, s20, s24
	s_addc_u32 s25, s21, s25
	s_and_b64 s[26:27], s[0:1], exec
	s_cselect_b32 s15, s25, s53
	s_cselect_b32 s19, s24, s52
	s_ashr_i32 s13, s12, 31
	s_lshl_b64 s[26:27], s[12:13], 19
	s_add_u32 s26, s62, s26
	s_addc_u32 s27, s63, s27
	s_and_b64 s[56:57], s[0:1], exec
	s_cselect_b32 s13, s27, s55
	s_cselect_b32 s29, s26, s54
	s_add_u32 s52, s52, 0xc000
	s_addc_u32 s53, s53, 0
	s_add_u32 s74, s54, 0x10000
	s_addc_u32 s75, s55, 0
	s_mov_b32 s76, -2
	v_mov_b64_e32 v[2:3], 0
	v_mov_b64_e32 v[4:5], 0
	v_mov_b64_e32 v[6:7], 0
	v_mov_b64_e32 v[8:9], 0
	v_mov_b64_e32 v[10:11], 0
	v_mov_b64_e32 v[12:13], 0
	v_mov_b64_e32 v[14:15], 0
	v_mov_b64_e32 v[16:17], 0
	v_mov_b64_e32 v[18:19], 0
	v_mov_b64_e32 v[20:21], 0
	v_mov_b64_e32 v[22:23], 0
	v_mov_b64_e32 v[24:25], 0
	v_mov_b64_e32 v[26:27], 0
	v_mov_b64_e32 v[28:29], 0
	v_mov_b64_e32 v[30:31], 0
	v_mov_b64_e32 v[32:33], 0
	v_mov_b64_e32 v[34:35], 0
	v_mov_b64_e32 v[36:37], 0
	v_mov_b64_e32 v[38:39], 0
	v_mov_b64_e32 v[40:41], 0
	v_mov_b64_e32 v[42:43], 0
	v_mov_b64_e32 v[44:45], 0
	v_mov_b64_e32 v[46:47], 0
	v_mov_b64_e32 v[48:49], 0
	v_mov_b64_e32 v[50:51], 0
	v_mov_b64_e32 v[52:53], 0
	v_mov_b64_e32 v[54:55], 0
	v_mov_b64_e32 v[56:57], 0
	v_mov_b64_e32 v[58:59], 0
	v_mov_b64_e32 v[60:61], 0
	v_mov_b64_e32 v[62:63], 0
	v_mov_b64_e32 v[64:65], 0
	v_mov_b64_e32 v[74:75], 0
	v_mov_b64_e32 v[76:77], 0
	v_mov_b64_e32 v[86:87], 0
	v_mov_b64_e32 v[88:89], 0
	v_mov_b64_e32 v[90:91], 0
	v_mov_b64_e32 v[92:93], 0
	v_mov_b64_e32 v[94:95], 0
	v_mov_b64_e32 v[96:97], 0
	v_mov_b64_e32 v[98:99], 0
	v_mov_b64_e32 v[100:101], 0
	v_mov_b64_e32 v[102:103], 0
	v_mov_b64_e32 v[104:105], 0
	v_mov_b64_e32 v[106:107], 0
	v_mov_b64_e32 v[108:109], 0
	v_mov_b64_e32 v[110:111], 0
	v_mov_b64_e32 v[112:113], 0
	v_mov_b64_e32 v[114:115], 0
	v_mov_b64_e32 v[116:117], 0
	v_mov_b64_e32 v[118:119], 0
	v_mov_b64_e32 v[120:121], 0
	v_mov_b64_e32 v[122:123], 0
	v_mov_b64_e32 v[124:125], 0
	v_mov_b64_e32 v[126:127], 0
	v_mov_b64_e32 v[128:129], 0
	v_mov_b64_e32 v[130:131], 0
	v_mov_b64_e32 v[132:133], 0
	v_mov_b64_e32 v[134:135], 0
	v_mov_b64_e32 v[136:137], 0
	v_mov_b64_e32 v[138:139], 0
	v_mov_b64_e32 v[140:141], 0
	v_mov_b64_e32 v[142:143], 0
	v_mov_b64_e32 v[144:145], 0

; template <class Epi, class Sched, bool ALIGN_EPI = false, bool SP2 = false, bool ATILED = false, bool BTILED = false>
; __device__ __forceinline__ void gemm_phase(PG8_LAS unsigned char* lds, const Gemm g, const Sched& S, const Epi& E, const int tid) {
;     ...
; #pragma unroll
;         for (int a = 0; a < 2; ++a)
; #pragma unroll
;             for (int b = 0; b < 2; ++b)
; #pragma unroll
;                 for (int m = 0; m < 4; ++m)
; #pragma unroll
;                     for (int n = 0; n < 2; ++n) acc[a][b][m][n] = (f32x4){0.f, 0.f, 0.f, 0.f};
;         cur = nxt; cA = nA; cB = nB; ++ui;
.LBB0_232:
	s_ashr_i32 s11, s10, 31
	v_cmp_lt_i64_e32 vcc, s[12:13], v[222:223]
	s_lshl_b64 s[12:13], s[10:11], 19
	v_readlane_b32 s14, v254, 57
	v_readlane_b32 s15, v254, 58
	s_add_u32 s12, s14, s12
	s_addc_u32 s13, s15, s13
	s_and_b64 s[14:15], vcc, exec
	s_cselect_b32 s11, s13, s29
	s_cselect_b32 s18, s12, s28
	s_ashr_i32 s9, s8, 31
	s_lshl_b64 s[14:15], s[8:9], 19
	s_add_u32 s14, s59, s14
	s_addc_u32 s15, s60, s15
	s_and_b64 s[54:55], vcc, exec
	s_cselect_b32 s9, s15, s53
	s_cselect_b32 s19, s14, s52
	s_add_u32 s28, s28, 0xc000
	s_addc_u32 s29, s29, 0
	s_add_u32 s25, s52, 0x10000
	s_addc_u32 s27, s53, 0
	s_mov_b32 s72, -2
	s_waitcnt lgkmcnt(0)
	v_mov_b64_e32 v[2:3], 0
	v_mov_b64_e32 v[4:5], 0
	v_mov_b64_e32 v[6:7], 0
	v_mov_b64_e32 v[8:9], 0
	v_mov_b64_e32 v[10:11], 0
	v_mov_b64_e32 v[12:13], 0
	v_mov_b64_e32 v[14:15], 0
	v_mov_b64_e32 v[16:17], 0
	v_mov_b64_e32 v[18:19], 0
	v_mov_b64_e32 v[20:21], 0
	v_mov_b64_e32 v[22:23], 0
	v_mov_b64_e32 v[24:25], 0
	v_mov_b64_e32 v[26:27], 0
	v_mov_b64_e32 v[28:29], 0
	v_mov_b64_e32 v[30:31], 0
	v_mov_b64_e32 v[32:33], 0
	v_mov_b64_e32 v[34:35], 0
	v_mov_b64_e32 v[36:37], 0
	v_mov_b64_e32 v[38:39], 0
	v_mov_b64_e32 v[40:41], 0
	v_mov_b64_e32 v[42:43], 0
	v_mov_b64_e32 v[44:45], 0
	v_mov_b64_e32 v[46:47], 0
	v_mov_b64_e32 v[48:49], 0
	v_mov_b64_e32 v[50:51], 0
	v_mov_b64_e32 v[52:53], 0
	v_mov_b64_e32 v[54:55], 0
	v_mov_b64_e32 v[56:57], 0
	v_mov_b64_e32 v[58:59], 0
	v_mov_b64_e32 v[60:61], 0
	v_mov_b64_e32 v[62:63], 0
	v_mov_b64_e32 v[64:65], 0
	v_mov_b64_e32 v[66:67], 0
	v_mov_b64_e32 v[68:69], 0
	v_mov_b64_e32 v[70:71], 0
	v_mov_b64_e32 v[72:73], 0
	v_mov_b64_e32 v[74:75], 0
	v_mov_b64_e32 v[76:77], 0
	v_mov_b64_e32 v[78:79], 0
	v_mov_b64_e32 v[80:81], 0
	v_mov_b64_e32 v[82:83], 0
	v_mov_b64_e32 v[84:85], 0
	v_mov_b64_e32 v[86:87], 0
	v_mov_b64_e32 v[88:89], 0
	v_mov_b64_e32 v[90:91], 0
	v_mov_b64_e32 v[92:93], 0
	v_mov_b64_e32 v[94:95], 0
	v_mov_b64_e32 v[96:97], 0
	v_mov_b64_e32 v[98:99], 0
	v_mov_b64_e32 v[100:101], 0
	v_mov_b64_e32 v[102:103], 0
	v_mov_b64_e32 v[104:105], 0
	v_mov_b64_e32 v[106:107], 0
	v_mov_b64_e32 v[108:109], 0
	v_mov_b64_e32 v[110:111], 0
	v_mov_b64_e32 v[112:113], 0
	v_mov_b64_e32 v[114:115], 0
	v_mov_b64_e32 v[116:117], 0
	v_mov_b64_e32 v[118:119], 0
	v_mov_b64_e32 v[120:121], 0
	v_mov_b64_e32 v[122:123], 0
	v_mov_b64_e32 v[124:125], 0
	v_mov_b64_e32 v[126:127], 0
	v_mov_b64_e32 v[128:129], 0

; #define GAS __attribute__((address_space(1)))
; __device__ __forceinline__ size_t PJ(int row, int col) { return ((size_t)(col >> 6) * SEQ + row) * 64 + (col & 63); }
; __device__ __forceinline__ void conv_phase(const GAS bf16_t* proj, const GAS float* cw, const GAS float* cb_, GAS bf16_t* mix, int tid, int G, int bid) {
;     ...
;         for (int r = 0; r < 6; ++r) { const int tt = t0 - 2 + r;
;             ccr[r] = (u32x4){0u, 0u, 0u, 0u}; cur[r] = (u32x4){0u, 0u, 0u, 0u};
;             if (tt >= 0) { ccr[r] = *(const GAS u32x4*)(proj + PJ(tt, C_CC + c8)); cur[r] = *(const GAS u32x4*)(proj + PJ(tt, C_CU + c8)); } }
.LBB0_445:
	s_or_b64 exec, exec, s[8:9]
	v_mov_b32_e32 v58, 0
	v_or_b32_e32 v10, 2, v2
	s_nop 0
	v_mov_b32_e32 v82, 0
	v_mov_b32_e32 v83, 0
	v_mov_b32_e32 v84, 0
	v_mov_b32_e32 v85, 0
	v_mov_b32_e32 v86, 0
	v_mov_b32_e32 v87, 0
	v_mov_b32_e32 v88, 0
	v_mov_b32_e32 v89, 0
	s_and_saveexec_b64 s[8:9], vcc
	s_cbranch_execz .LBB0_447
	v_mov_b32_e32 v11, v179
	v_lshlrev_b64 v[12:13], 7, v[10:11]
	v_lshl_add_u64 v[16:17], v[6:7], 0, v[12:13]
	v_lshl_add_u64 v[12:13], v[4:5], 0, v[12:13]
	global_load_dwordx4 v[86:89], v[12:13], off
	global_load_dwordx4 v[82:85], v[16:17], off

; template <class Epi, class Sched, bool ALIGN_EPI = false, bool SP2 = false, bool ATILED = false, bool BTILED = false>
; __device__ __forceinline__ void gemm_phase(PG8_LAS unsigned char* lds, const Gemm g, const Sched& S, const Epi& E, const int tid) {
;     ...
; #pragma unroll
;         for (int a = 0; a < 2; ++a)
; #pragma unroll
;             for (int b = 0; b < 2; ++b)
; #pragma unroll
;                 for (int m = 0; m < 4; ++m)
; #pragma unroll
;                     for (int n = 0; n < 2; ++n) acc[a][b][m][n] = (f32x4){0.f, 0.f, 0.f, 0.f};
;         cur = nxt; cA = nA; cB = nB; ++ui;
.LBB0_477:
	s_add_u32 s16, s16, 0xc000
	s_addc_u32 s17, s17, 0
	s_add_u32 s67, s18, 0x10000
	s_addc_u32 s68, s19, 0
	s_mov_b32 s69, -2
	s_waitcnt lgkmcnt(0)
	v_mov_b64_e32 v[2:3], 0
	v_mov_b64_e32 v[4:5], 0
	v_mov_b64_e32 v[6:7], 0
	v_mov_b64_e32 v[8:9], 0
	v_mov_b64_e32 v[10:11], 0
	v_mov_b64_e32 v[12:13], 0
	v_mov_b64_e32 v[14:15], 0
	v_mov_b64_e32 v[16:17], 0
	v_mov_b64_e32 v[18:19], 0
	v_mov_b64_e32 v[20:21], 0
	v_mov_b64_e32 v[22:23], 0
	v_mov_b64_e32 v[24:25], 0
	v_mov_b64_e32 v[26:27], 0
	v_mov_b64_e32 v[28:29], 0
	v_mov_b64_e32 v[30:31], 0
	v_mov_b64_e32 v[32:33], 0
	v_mov_b64_e32 v[34:35], 0
	v_mov_b64_e32 v[36:37], 0
	v_mov_b64_e32 v[38:39], 0
	v_mov_b64_e32 v[40:41], 0
	v_mov_b64_e32 v[42:43], 0
	v_mov_b64_e32 v[44:45], 0
	v_mov_b64_e32 v[46:47], 0
	v_mov_b64_e32 v[48:49], 0
	v_mov_b64_e32 v[50:51], 0
	v_mov_b64_e32 v[52:53], 0
	v_mov_b64_e32 v[54:55], 0
	v_mov_b64_e32 v[56:57], 0
	v_mov_b64_e32 v[58:59], 0
	v_mov_b64_e32 v[60:61], 0
	v_mov_b64_e32 v[62:63], 0
	v_mov_b64_e32 v[64:65], 0
	v_mov_b64_e32 v[66:67], 0
	v_mov_b64_e32 v[68:69], 0
	v_mov_b64_e32 v[70:71], 0
	v_mov_b64_e32 v[72:73], 0
	v_mov_b64_e32 v[74:75], 0
	v_mov_b64_e32 v[76:77], 0
	v_mov_b64_e32 v[78:79], 0
	v_mov_b64_e32 v[80:81], 0
	v_mov_b64_e32 v[82:83], 0
	v_mov_b64_e32 v[84:85], 0
	v_mov_b64_e32 v[86:87], 0
	v_mov_b64_e32 v[88:89], 0
	v_mov_b64_e32 v[90:91], 0
	v_mov_b64_e32 v[92:93], 0
	v_mov_b64_e32 v[94:95], 0
	v_mov_b64_e32 v[96:97], 0
	v_mov_b64_e32 v[98:99], 0
	v_mov_b64_e32 v[100:101], 0
	v_mov_b64_e32 v[102:103], 0
	v_mov_b64_e32 v[104:105], 0
	v_mov_b64_e32 v[106:107], 0
	v_mov_b64_e32 v[108:109], 0
	v_mov_b64_e32 v[110:111], 0
	v_mov_b64_e32 v[112:113], 0
	v_mov_b64_e32 v[114:115], 0
	v_mov_b64_e32 v[116:117], 0
	v_mov_b64_e32 v[118:119], 0
	v_mov_b64_e32 v[120:121], 0
	v_mov_b64_e32 v[122:123], 0
	v_mov_b64_e32 v[124:125], 0
	v_mov_b64_e32 v[126:127], 0
	v_mov_b64_e32 v[128:129], 0

; template <class Epi, class Sched, bool ALIGN_EPI = false, bool SP2 = false, bool ATILED = false, bool BTILED = false>
; __device__ __forceinline__ void gemm_phase(PG8_LAS unsigned char* lds, const Gemm g, const Sched& S, const Epi& E, const int tid) {
;     ...
; #pragma unroll
;         for (int a = 0; a < 2; ++a)
; #pragma unroll
;             for (int b = 0; b < 2; ++b)
; #pragma unroll
;                 for (int m = 0; m < 4; ++m)
; #pragma unroll
;                     for (int n = 0; n < 2; ++n) acc[a][b][m][n] = (f32x4){0.f, 0.f, 0.f, 0.f};
;         cur = nxt; cA = nA; cB = nB; ++ui;
.LBB0_523:
	s_add_u32 s12, s12, 0xc000
	s_addc_u32 s13, s13, 0
	s_add_u32 s63, s14, 0x10000
	s_addc_u32 s64, s15, 0
	s_mov_b32 s65, -2
	v_mov_b64_e32 v[2:3], 0
	v_mov_b64_e32 v[4:5], 0
	v_mov_b64_e32 v[6:7], 0
	v_mov_b64_e32 v[8:9], 0
	v_mov_b64_e32 v[10:11], 0
	v_mov_b64_e32 v[12:13], 0
	v_mov_b64_e32 v[14:15], 0
	v_mov_b64_e32 v[16:17], 0
	v_mov_b64_e32 v[18:19], 0
	v_mov_b64_e32 v[20:21], 0
	v_mov_b64_e32 v[22:23], 0
	v_mov_b64_e32 v[24:25], 0
	v_mov_b64_e32 v[26:27], 0
	v_mov_b64_e32 v[28:29], 0
	v_mov_b64_e32 v[30:31], 0
	v_mov_b64_e32 v[32:33], 0
	v_mov_b64_e32 v[34:35], 0
	v_mov_b64_e32 v[36:37], 0
	v_mov_b64_e32 v[38:39], 0
	v_mov_b64_e32 v[40:41], 0
	v_mov_b64_e32 v[42:43], 0
	v_mov_b64_e32 v[44:45], 0
	v_mov_b64_e32 v[46:47], 0
	v_mov_b64_e32 v[48:49], 0
	v_mov_b64_e32 v[50:51], 0
	v_mov_b64_e32 v[52:53], 0
	v_mov_b64_e32 v[54:55], 0
	v_mov_b64_e32 v[56:57], 0
	v_mov_b64_e32 v[58:59], 0
	v_mov_b64_e32 v[60:61], 0
	v_mov_b64_e32 v[62:63], 0
	v_mov_b64_e32 v[64:65], 0
	v_mov_b64_e32 v[66:67], 0
	v_mov_b64_e32 v[68:69], 0
	v_mov_b64_e32 v[70:71], 0
	v_mov_b64_e32 v[72:73], 0
	v_mov_b64_e32 v[74:75], 0
	v_mov_b64_e32 v[76:77], 0
	v_mov_b64_e32 v[78:79], 0
	v_mov_b64_e32 v[80:81], 0
	v_mov_b64_e32 v[82:83], 0
	v_mov_b64_e32 v[84:85], 0
	v_mov_b64_e32 v[86:87], 0
	v_mov_b64_e32 v[88:89], 0
	v_mov_b64_e32 v[90:91], 0
	v_mov_b64_e32 v[92:93], 0
	v_mov_b64_e32 v[94:95], 0
	v_mov_b64_e32 v[96:97], 0
	v_mov_b64_e32 v[98:99], 0
	v_mov_b64_e32 v[100:101], 0
	v_mov_b64_e32 v[102:103], 0
	v_mov_b64_e32 v[104:105], 0
	v_mov_b64_e32 v[106:107], 0
	v_mov_b64_e32 v[108:109], 0
	v_mov_b64_e32 v[110:111], 0
	v_mov_b64_e32 v[112:113], 0
	v_mov_b64_e32 v[114:115], 0
	v_mov_b64_e32 v[116:117], 0
	v_mov_b64_e32 v[118:119], 0
	v_mov_b64_e32 v[120:121], 0
	v_mov_b64_e32 v[122:123], 0
	v_mov_b64_e32 v[124:125], 0
	v_mov_b64_e32 v[126:127], 0
	v_mov_b64_e32 v[128:129], 0

; template <class Epi, class Sched, bool ALIGN_EPI = false, bool SP2 = false, bool ATILED = false, bool BTILED = false>
; __device__ __forceinline__ void gemm_phase(PG8_LAS unsigned char* lds, const Gemm g, const Sched& S, const Epi& E, const int tid) {
;     ...
;         const bool has_next = S.next(ui + 1, nxt);
;         const char* nA = has_next ? (const char*)g.A + (size_t)nxt.pm * tstepA : cA; const char* nB = has_next ? (const char*)g.Bt + (size_t)nxt.pn * tstepB : cB;
;         for (int t = 0; t < nt; t += 2) {
;             const bool last = (t == nt - 2);
;             const char* a1 = cA + (size_t)(t + 1) * kstepA;
;             const char* a2 = last ? nA : cA + (size_t)(t + 2) * kstepA; const char* b2 = last ? nB : cB + (size_t)(t + 2) * kstepB;
;             const char* a3 = a2 + kstepA; const char* b3 = b2 + kstepB;
;     ...
; #pragma unroll
;         for (int a = 0; a < 2; ++a)
; #pragma unroll
;             for (int b = 0; b < 2; ++b)
; #pragma unroll
;                 for (int m = 0; m < 4; ++m)
; #pragma unroll
;                     for (int n = 0; n < 2; ++n) acc[a][b][m][n] = (f32x4){0.f, 0.f, 0.f, 0.f};
;         cur = nxt; cA = nA; cB = nB; ++ui;
.LBB0_552:
	s_ashr_i32 s17, s16, 31
	s_lshl_b64 s[18:19], s[16:17], 19
	s_add_u32 s18, s20, s18
	s_addc_u32 s19, s21, s19
	s_and_b64 s[22:23], s[0:1], exec
	s_cselect_b32 s3, s19, s25
	s_cselect_b32 s5, s18, s24
	s_ashr_i32 s15, s14, 31
	s_lshl_b64 s[22:23], s[14:15], 19
	s_add_u32 s22, s58, s22
	s_addc_u32 s23, s59, s23
	s_and_b64 s[28:29], s[0:1], exec
	s_cselect_b32 s15, s23, s27
	s_cselect_b32 s17, s22, s26
	s_add_u32 s24, s24, 0xc000
	s_addc_u32 s25, s25, 0
	s_add_u32 s30, s26, 0x10000
	s_addc_u32 s54, s27, 0
	s_mov_b32 s55, -2
	v_mov_b64_e32 v[2:3], 0
	v_mov_b64_e32 v[4:5], 0
	v_mov_b64_e32 v[6:7], 0
	v_mov_b64_e32 v[8:9], 0
	v_mov_b64_e32 v[10:11], 0
	v_mov_b64_e32 v[12:13], 0
	v_mov_b64_e32 v[14:15], 0
	v_mov_b64_e32 v[16:17], 0
	v_mov_b64_e32 v[18:19], 0
	v_mov_b64_e32 v[20:21], 0
	v_mov_b64_e32 v[22:23], 0
	v_mov_b64_e32 v[24:25], 0
	v_mov_b64_e32 v[26:27], 0
	v_mov_b64_e32 v[28:29], 0
	v_mov_b64_e32 v[30:31], 0
	v_mov_b64_e32 v[32:33], 0
	v_mov_b64_e32 v[34:35], 0
	v_mov_b64_e32 v[36:37], 0
	v_mov_b64_e32 v[38:39], 0
	v_mov_b64_e32 v[40:41], 0
	v_mov_b64_e32 v[42:43], 0
	v_mov_b64_e32 v[44:45], 0
	v_mov_b64_e32 v[46:47], 0
	v_mov_b64_e32 v[48:49], 0
	v_mov_b64_e32 v[50:51], 0
	v_mov_b64_e32 v[52:53], 0
	v_mov_b64_e32 v[54:55], 0
	v_mov_b64_e32 v[56:57], 0
	v_mov_b64_e32 v[58:59], 0
	v_mov_b64_e32 v[60:61], 0
	v_mov_b64_e32 v[62:63], 0
	v_mov_b64_e32 v[64:65], 0
	v_mov_b64_e32 v[90:91], 0
	v_mov_b64_e32 v[92:93], 0
	v_mov_b64_e32 v[94:95], 0
	v_mov_b64_e32 v[96:97], 0
	v_mov_b64_e32 v[98:99], 0
	v_mov_b64_e32 v[100:101], 0
	v_mov_b64_e32 v[102:103], 0
	v_mov_b64_e32 v[104:105], 0
	v_mov_b64_e32 v[114:115], 0
	v_mov_b64_e32 v[116:117], 0
	v_mov_b64_e32 v[118:119], 0
	v_mov_b64_e32 v[120:121], 0
	v_mov_b64_e32 v[122:123], 0
	v_mov_b64_e32 v[124:125], 0
	v_mov_b64_e32 v[126:127], 0
	v_mov_b64_e32 v[128:129], 0
	v_mov_b64_e32 v[138:139], 0
	v_mov_b64_e32 v[140:141], 0
	v_mov_b64_e32 v[142:143], 0
	v_mov_b64_e32 v[144:145], 0
	v_mov_b64_e32 v[150:151], 0
	v_mov_b64_e32 v[152:153], 0
	v_mov_b64_e32 v[154:155], 0
	v_mov_b64_e32 v[156:157], 0
	v_mov_b64_e32 v[162:163], 0
	v_mov_b64_e32 v[164:165], 0
	v_mov_b64_e32 v[166:167], 0
	v_mov_b64_e32 v[168:169], 0
	v_mov_b64_e32 v[170:171], 0
	v_mov_b64_e32 v[172:173], 0
	v_mov_b64_e32 v[174:175], 0
	v_mov_b64_e32 v[176:177], 0
